# v40: v37 + 16-byte stores of the token / qkv / mixer / scan phases write-through (barriers still write back L2)
# baseline (speedup 1.0000x reference)
.LBB0_2696:
	v_pk_add_f32 v[6:7], v[10:11], v[6:7]
	v_pk_add_f32 v[8:9], v[12:13], v[8:9]
	v_pk_fma_f32 v[6:7], v[6:7], 0.5, v[2:3] op_sel_hi:[1,0,1] neg_lo:[0,0,1] neg_hi:[0,0,1]
	v_xor_b32_e32 v11, 0x80000000, v5
	v_pk_fma_f32 v[2:3], v[14:15], v[6:7], v[2:3]
	v_cvt_pk_bf16_f32 v6, v149, s0
	v_cvt_pk_bf16_f32 v7, v147, s0
	global_store_short v[174:175], v7, off offset:512
	global_store_short v[174:175], v6, off offset:640
	v_cvt_pk_bf16_f32 v6, v145, s0
	v_xor_b32_e32 v10, 0x80000000, v4
	global_store_short v[174:175], v6, off offset:768
	v_cvt_pk_bf16_f32 v6, v143, s0
	v_pk_fma_f32 v[8:9], v[8:9], 0.5, v[10:11] op_sel_hi:[1,0,1]
	global_store_short v[174:175], v6, off offset:896
	v_lshl_add_u64 v[6:7], s[14:15], 0, v[166:167]
	v_pk_add_f32 v[22:23], v[26:27], v[22:23]
	v_pk_add_f32 v[24:25], v[28:29], v[24:25]
	v_xor_b32_e32 v27, 0x80000000, v21
	v_xor_b32_e32 v26, 0x80000000, v20
	v_pk_fma_f32 v[4:5], v[16:17], v[8:9], v[4:5]
	v_add_co_u32_e32 v8, vcc, s39, v6
	v_pk_add_f32 v[38:39], v[42:43], v[38:39]
	v_pk_add_f32 v[40:41], v[44:45], v[40:41]
	v_xor_b32_e32 v43, 0x80000000, v37
	v_xor_b32_e32 v42, 0x80000000, v36
	v_pk_fma_f32 v[24:25], v[24:25], 0.5, v[26:27] op_sel_hi:[1,0,1]
	v_pk_fma_f32 v[22:23], v[22:23], 0.5, v[18:19] op_sel_hi:[1,0,1] neg_lo:[0,0,1] neg_hi:[0,0,1]
	v_addc_co_u32_e32 v9, vcc, 0, v7, vcc
	v_pk_add_f32 v[54:55], v[58:59], v[54:55]
	v_pk_add_f32 v[56:57], v[60:61], v[56:57]
	v_xor_b32_e32 v59, 0x80000000, v53
	v_xor_b32_e32 v58, 0x80000000, v52
	v_pk_fma_f32 v[40:41], v[40:41], 0.5, v[42:43] op_sel_hi:[1,0,1]
	v_pk_fma_f32 v[38:39], v[38:39], 0.5, v[34:35] op_sel_hi:[1,0,1] neg_lo:[0,0,1] neg_hi:[0,0,1]
	v_pk_fma_f32 v[20:21], v[32:33], v[24:25], v[20:21]
	v_pk_fma_f32 v[18:19], v[30:31], v[22:23], v[18:19]
	global_store_dwordx4 v[8:9], v[2:5], off sc1
	global_store_dwordx4 v[8:9], v[18:21], off offset:16 sc1
	v_pk_fma_f32 v[56:57], v[56:57], 0.5, v[58:59] op_sel_hi:[1,0,1]
	v_add_co_u32_e32 v2, vcc, s41, v6
	v_pk_fma_f32 v[54:55], v[54:55], 0.5, v[50:51] op_sel_hi:[1,0,1] neg_lo:[0,0,1] neg_hi:[0,0,1]
	v_pk_fma_f32 v[36:37], v[48:49], v[40:41], v[36:37]
	v_pk_fma_f32 v[34:35], v[46:47], v[38:39], v[34:35]
	v_addc_co_u32_e32 v3, vcc, 0, v7, vcc
	v_pk_fma_f32 v[52:53], v[64:65], v[56:57], v[52:53]
	v_pk_fma_f32 v[50:51], v[62:63], v[54:55], v[50:51]
	global_store_dwordx4 v[2:3], v[34:37], off sc1
	global_store_dwordx4 v[2:3], v[50:53], off offset:16 sc1
	v_pk_mul_f32 v[2:3], v[36:37], v[108:109]
	v_pk_mul_f32 v[8:9], v[34:35], v[106:107]
	v_pk_mul_f32 v[4:5], v[2:3], v[2:3]
	v_pk_mul_f32 v[14:15], v[8:9], v[8:9]
	v_pk_mul_f32 v[10:11], v[52:53], v[100:101]
	v_pk_mul_f32 v[12:13], v[50:51], v[98:99]
	v_pk_mov_b32 v[16:17], v[14:15], v[4:5] op_sel:[1,0]
	v_mov_b32_e32 v15, v5
	v_pk_add_f32 v[4:5], v[16:17], v[14:15]
	v_pk_mul_f32 v[14:15], v[10:11], v[10:11]
	v_pk_mul_f32 v[16:17], v[12:13], v[12:13]
	v_mov_b32_e32 v18, v14
	v_mov_b32_e32 v19, v16
	v_mov_b32_e32 v16, v15
	v_pk_add_f32 v[14:15], v[18:19], v[16:17]
	v_add_f32_e32 v4, v4, v5
	v_add_f32_e32 v4, v4, v15
	v_add_f32_e32 v4, v14, v4
	v_pk_add_f32 v[70:71], v[74:75], v[70:71]
	v_pk_add_f32 v[72:73], v[76:77], v[72:73]
	v_add_f32_dpp v4, v4, v4 quad_perm:[1,0,3,2] row_mask:0xf bank_mask:0xf bound_ctrl:1
	v_xor_b32_e32 v75, 0x80000000, v69
	v_xor_b32_e32 v74, 0x80000000, v68
	v_add_f32_dpp v4, v4, v4 quad_perm:[2,3,0,1] row_mask:0xf bank_mask:0xf bound_ctrl:1
	v_pk_add_f32 v[86:87], v[90:91], v[86:87]
	v_pk_add_f32 v[88:89], v[92:93], v[88:89]
	v_add_f32_dpp v4, v4, v4 row_half_mirror row_mask:0xf bank_mask:0xf bound_ctrl:1
	v_add_f32_e32 v4, 0x358637bd, v4
	v_mul_f32_e32 v5, 0x4b800000, v4
	v_cmp_gt_f32_e32 vcc, s23, v4
	v_xor_b32_e32 v91, 0x80000000, v85
	v_xor_b32_e32 v90, 0x80000000, v84
	v_cndmask_b32_e32 v4, v4, v5, vcc
	v_rsq_f32_e32 v14, v4
	v_pk_fma_f32 v[72:73], v[72:73], 0.5, v[74:75] op_sel_hi:[1,0,1]
	v_pk_fma_f32 v[70:71], v[70:71], 0.5, v[66:67] op_sel_hi:[1,0,1] neg_lo:[0,0,1] neg_hi:[0,0,1]
	v_add_co_u32_e64 v4, s[8:9], s48, v6
	v_pk_fma_f32 v[88:89], v[88:89], 0.5, v[90:91] op_sel_hi:[1,0,1]
	v_pk_fma_f32 v[86:87], v[86:87], 0.5, v[82:83] op_sel_hi:[1,0,1] neg_lo:[0,0,1] neg_hi:[0,0,1]
	v_pk_fma_f32 v[68:69], v[80:81], v[72:73], v[68:69]
	v_pk_fma_f32 v[66:67], v[78:79], v[70:71], v[66:67]
	v_addc_co_u32_e64 v5, s[8:9], 0, v7, s[8:9]
	v_pk_fma_f32 v[84:85], v[96:97], v[88:89], v[84:85]
	v_pk_fma_f32 v[82:83], v[94:95], v[86:87], v[82:83]
	global_store_dwordx4 v[4:5], v[66:69], off sc1
	global_store_dwordx4 v[4:5], v[82:85], off offset:16 sc1
	v_mul_f32_e32 v4, 0x45800000, v14
	v_cndmask_b32_e32 v14, v14, v4, vcc
	v_add_co_u32_e32 v6, vcc, 0xd528000, v6
	v_pk_add_f32 v[110:111], v[114:115], v[110:111]
	v_pk_add_f32 v[112:113], v[116:117], v[112:113]
	v_xor_b32_e32 v115, 0x80000000, v105
	v_xor_b32_e32 v114, 0x80000000, v104
	v_pk_mul_f32 v[4:5], v[2:3], v[14:15] op_sel_hi:[1,0]
	v_pk_mul_f32 v[2:3], v[8:9], v[14:15] op_sel_hi:[1,0]
	v_addc_co_u32_e32 v7, vcc, 0, v7, vcc
	v_pk_fma_f32 v[112:113], v[112:113], 0.5, v[114:115] op_sel_hi:[1,0,1]
	v_pk_fma_f32 v[110:111], v[110:111], 0.5, v[102:103] op_sel_hi:[1,0,1] neg_lo:[0,0,1] neg_hi:[0,0,1]
	global_store_dwordx4 v[6:7], v[2:5], off sc1
	v_pk_fma_f32 v[104:105], v[120:121], v[112:113], v[104:105]
	v_pk_fma_f32 v[102:103], v[118:119], v[110:111], v[102:103]
	v_pk_mul_f32 v[4:5], v[10:11], v[14:15] op_sel_hi:[1,0]
	v_pk_mul_f32 v[2:3], v[12:13], v[14:15] op_sel_hi:[1,0]
	global_store_dwordx4 v[6:7], v[2:5], off offset:16 sc1
	s_nop 1
	v_lshl_add_u64 v[2:3], s[14:15], 0, v[156:157]
	s_and_saveexec_b64 s[8:9], s[4:5]
	s_xor_b64 s[8:9], exec, s[8:9]
	s_cbranch_execnz .LBB0_2699
	s_andn2_saveexec_b64 s[8:9], s[8:9]
	s_cbranch_execnz .LBB0_2700

.Lsgp1_issue:
	v_lshl_add_u64 v[208:209], v[208:209], 0, v[34:35]
	s_mov_b32 m0, s19
	s_nop 0
	global_load_lds_dwordx4 v[208:209], off
	v_lshl_add_u64 v[210:211], v[210:211], 0, v[34:35]
	s_mov_b32 m0, s20
	s_nop 0
	global_load_lds_dwordx4 v[210:211], off
	v_lshl_add_u64 v[212:213], v[212:213], 0, v[34:35]
	s_mov_b32 m0, s21
	s_nop 0
	global_load_lds_dwordx4 v[212:213], off
	v_lshl_add_u64 v[214:215], v[214:215], 0, v[34:35]
	s_mov_b32 m0, s22
	s_nop 0
	global_load_lds_dwordx4 v[214:215], off
	v_mfma_f32_16x16x32_bf16 v[52:55], v[6:9], v[48:51], v[52:55]
	v_add_u32_e32 v36, 48, v36
	s_add_i32 s12, s12, s56
	s_add_i32 s17, s17, s18
	v_mfma_f32_16x16x32_bf16 v[48:51], v[2:5], v[48:51], v[56:59]
	s_cmpk_lt_i32 s12, 0xc0
	v_mfma_f32_16x16x32_bf16 v[56:59], v[6:9], v[60:63], v[64:67]
	s_nop 2
	s_waitcnt vmcnt(4)
	s_nop 1
	v_mov_b64_e32 v[64:65], v[200:201]
	v_mov_b64_e32 v[66:67], v[202:203]
	v_mfma_f32_16x16x32_bf16 v[60:63], v[2:5], v[60:63], v[68:71]
	s_nop 0
	v_add_f32_e32 v37, v52, v64
	v_add_f32_e32 v47, v53, v65
	v_add_f32_e32 v52, v54, v66
	v_add_f32_e32 v53, v55, v67
	v_mul_f32_e32 v37, 0xbfb8aa3b, v37
	v_mul_f32_e32 v47, 0xbfb8aa3b, v47
	v_mul_f32_e32 v52, 0xbfb8aa3b, v52
	v_mul_f32_e32 v53, 0xbfb8aa3b, v53
	v_exp_f32_e32 v37, v37
	v_exp_f32_e32 v47, v47
	v_exp_f32_e32 v52, v52
	v_exp_f32_e32 v53, v53
	v_add_f32_e32 v37, 1.0, v37
	v_add_f32_e32 v47, 1.0, v47
	v_add_f32_e32 v52, 1.0, v52
	v_add_f32_e32 v53, 1.0, v53
	v_rcp_f32_e32 v37, v37
	v_rcp_f32_e32 v47, v47
	v_rcp_f32_e32 v52, v52
	v_rcp_f32_e32 v53, v53
	v_mul_f32_e32 v37, 0xbf1b4598, v37
	v_mul_f32_e32 v47, 0xbf1b4598, v47
	v_mul_f32_e32 v52, 0xbf1b4598, v52
	v_mul_f32_e32 v53, 0xbf1b4598, v53
	v_mul_f32_e32 v37, 0x3fb8aa3b, v37
	v_mul_f32_e32 v47, 0x3fb8aa3b, v47
	v_mul_f32_e32 v54, 0x3fb8aa3b, v52
	v_mul_f32_e32 v55, 0x3fb8aa3b, v53
	v_exp_f32_e32 v52, v37
	v_exp_f32_e32 v53, v47
	v_exp_f32_e32 v54, v54
	v_exp_f32_e32 v55, v55
	s_waitcnt lgkmcnt(1)
	v_mfma_f32_16x16x32_bf16 v[18:21], v[18:21], v[22:25], 0
	global_store_dwordx4 v[88:89], v[52:55], off sc1
	s_nop 1
	v_mov_b64_e32 v[52:53], v[204:205]
	v_mov_b64_e32 v[54:55], v[206:207]
	v_mfma_f32_16x16x32_bf16 v[10:13], v[10:13], v[22:25], 0
	s_nop 0
	v_add_f32_e32 v37, v48, v52
	v_add_f32_e32 v47, v49, v53
	v_add_f32_e32 v48, v50, v54
	v_add_f32_e32 v49, v51, v55
	v_mul_f32_e32 v37, 0xbfb8aa3b, v37
	v_mul_f32_e32 v47, 0xbfb8aa3b, v47
	v_mul_f32_e32 v48, 0xbfb8aa3b, v48
	v_mul_f32_e32 v49, 0xbfb8aa3b, v49
	v_exp_f32_e32 v37, v37
	v_exp_f32_e32 v47, v47
	v_exp_f32_e32 v48, v48
	v_exp_f32_e32 v49, v49
	v_add_f32_e32 v37, 1.0, v37
	v_add_f32_e32 v47, 1.0, v47
	v_add_f32_e32 v48, 1.0, v48
	v_add_f32_e32 v49, 1.0, v49
	v_rcp_f32_e32 v37, v37
	v_rcp_f32_e32 v47, v47
	v_rcp_f32_e32 v48, v48
	v_rcp_f32_e32 v49, v49
	v_mul_f32_e32 v37, 0xbf1b4598, v37
	v_mul_f32_e32 v47, 0xbf1b4598, v47
	v_mul_f32_e32 v48, 0xbf1b4598, v48
	v_mul_f32_e32 v49, 0xbf1b4598, v49
	v_mul_f32_e32 v37, 0x3fb8aa3b, v37
	v_mul_f32_e32 v47, 0x3fb8aa3b, v47
	v_mul_f32_e32 v50, 0x3fb8aa3b, v48
	v_mul_f32_e32 v51, 0x3fb8aa3b, v49
	v_exp_f32_e32 v48, v37
	v_exp_f32_e32 v49, v47
	v_exp_f32_e32 v50, v50
	v_exp_f32_e32 v51, v51
	v_lshlrev_b64 v[52:53], 11, v[86:87]
	v_lshl_add_u64 v[52:53], s[4:5], 0, v[52:53]
	global_store_dwordx4 v[88:89], v[48:51], off offset:64 sc1
	s_nop 1
	v_mov_b64_e32 v[48:49], v[200:201]
	v_mov_b64_e32 v[50:51], v[202:203]
	s_nop 0
	v_add_f32_e32 v37, v56, v48
	v_add_f32_e32 v47, v57, v49
	v_add_f32_e32 v48, v58, v50
	v_add_f32_e32 v49, v59, v51
	v_mul_f32_e32 v37, 0xbfb8aa3b, v37
	v_mul_f32_e32 v47, 0xbfb8aa3b, v47
	v_mul_f32_e32 v48, 0xbfb8aa3b, v48
	v_mul_f32_e32 v49, 0xbfb8aa3b, v49
	v_exp_f32_e32 v37, v37
	v_exp_f32_e32 v47, v47
	v_exp_f32_e32 v48, v48
	v_exp_f32_e32 v49, v49
	v_add_f32_e32 v37, 1.0, v37
	v_add_f32_e32 v47, 1.0, v47
	v_add_f32_e32 v48, 1.0, v48
	v_add_f32_e32 v49, 1.0, v49
	v_rcp_f32_e32 v37, v37
	v_rcp_f32_e32 v47, v47
	v_rcp_f32_e32 v48, v48
	v_rcp_f32_e32 v49, v49
	v_mul_f32_e32 v37, 0xbf1b4598, v37
	v_mul_f32_e32 v47, 0xbf1b4598, v47
	v_mul_f32_e32 v48, 0xbf1b4598, v48
	v_mul_f32_e32 v49, 0xbf1b4598, v49
	v_mul_f32_e32 v37, 0x3fb8aa3b, v37
	v_mul_f32_e32 v47, 0x3fb8aa3b, v47
	v_mul_f32_e32 v50, 0x3fb8aa3b, v48
	v_mul_f32_e32 v51, 0x3fb8aa3b, v49
	v_exp_f32_e32 v48, v37
	v_exp_f32_e32 v49, v47
	v_exp_f32_e32 v50, v50
	v_exp_f32_e32 v51, v51
	v_lshl_add_u64 v[56:57], v[52:53], 0, v[38:39]
	v_mfma_f32_16x16x32_bf16 v[52:55], v[6:9], v[72:75], v[76:79]
	global_store_dwordx4 v[84:85], v[48:51], off sc1
	s_nop 1
	v_mov_b64_e32 v[48:49], v[204:205]
	v_mov_b64_e32 v[50:51], v[206:207]
	s_waitcnt lgkmcnt(0)
	v_mfma_f32_16x16x32_bf16 v[6:9], v[6:9], v[14:17], v[18:21]
	s_nop 0
	v_add_f32_e32 v37, v60, v48
	v_add_f32_e32 v47, v61, v49
	v_add_f32_e32 v48, v62, v50
	v_add_f32_e32 v49, v63, v51
	v_mul_f32_e32 v37, 0xbfb8aa3b, v37
	v_mul_f32_e32 v47, 0xbfb8aa3b, v47
	v_mul_f32_e32 v48, 0xbfb8aa3b, v48
	v_mul_f32_e32 v49, 0xbfb8aa3b, v49
	v_exp_f32_e32 v37, v37
	v_exp_f32_e32 v47, v47
	v_exp_f32_e32 v48, v48
	v_exp_f32_e32 v49, v49
	v_add_f32_e32 v37, 1.0, v37
	v_add_f32_e32 v47, 1.0, v47
	v_add_f32_e32 v48, 1.0, v48
	v_add_f32_e32 v49, 1.0, v49
	v_rcp_f32_e32 v37, v37
	v_rcp_f32_e32 v47, v47
	v_rcp_f32_e32 v48, v48
	v_rcp_f32_e32 v49, v49
	v_mul_f32_e32 v37, 0xbf1b4598, v37
	v_mul_f32_e32 v47, 0xbf1b4598, v47
	v_mul_f32_e32 v48, 0xbf1b4598, v48
	v_mul_f32_e32 v49, 0xbf1b4598, v49
	v_mul_f32_e32 v37, 0x3fb8aa3b, v37
	v_mul_f32_e32 v47, 0x3fb8aa3b, v47
	v_mul_f32_e32 v50, 0x3fb8aa3b, v48
	v_mul_f32_e32 v51, 0x3fb8aa3b, v49
	v_exp_f32_e32 v48, v37
	v_exp_f32_e32 v49, v47
	v_exp_f32_e32 v50, v50
	v_exp_f32_e32 v51, v51
	global_store_dwordx4 v[84:85], v[48:51], off offset:64 sc1
	s_nop 1
	v_mov_b64_e32 v[48:49], v[200:201]
	v_mov_b64_e32 v[50:51], v[202:203]
	s_nop 0
	v_add_f32_e32 v37, v52, v48
	v_add_f32_e32 v47, v53, v49
	v_add_f32_e32 v48, v54, v50
	v_add_f32_e32 v49, v55, v51
	v_mul_f32_e32 v37, 0xbfb8aa3b, v37
	v_mul_f32_e32 v47, 0xbfb8aa3b, v47
	v_mul_f32_e32 v48, 0xbfb8aa3b, v48
	v_mul_f32_e32 v49, 0xbfb8aa3b, v49
	v_exp_f32_e32 v37, v37
	v_exp_f32_e32 v47, v47
	v_exp_f32_e32 v48, v48
	v_exp_f32_e32 v49, v49
	v_add_f32_e32 v37, 1.0, v37
	v_add_f32_e32 v47, 1.0, v47
	v_add_f32_e32 v48, 1.0, v48
	v_add_f32_e32 v49, 1.0, v49
	v_rcp_f32_e32 v37, v37
	v_rcp_f32_e32 v47, v47
	v_rcp_f32_e32 v48, v48
	v_rcp_f32_e32 v49, v49
	v_mul_f32_e32 v37, 0xbf1b4598, v37
	v_mul_f32_e32 v47, 0xbf1b4598, v47
	v_mul_f32_e32 v48, 0xbf1b4598, v48
	v_mul_f32_e32 v49, 0xbf1b4598, v49
	v_mul_f32_e32 v37, 0x3fb8aa3b, v37
	v_mul_f32_e32 v47, 0x3fb8aa3b, v47
	v_mul_f32_e32 v50, 0x3fb8aa3b, v48
	v_mul_f32_e32 v51, 0x3fb8aa3b, v49
	v_exp_f32_e32 v48, v37
	v_exp_f32_e32 v49, v47
	v_exp_f32_e32 v50, v50
	v_exp_f32_e32 v51, v51
	v_mfma_f32_16x16x32_bf16 v[52:55], v[2:5], v[72:75], v[80:83]
	global_store_dwordx4 v[56:57], v[48:51], off sc1
	s_nop 1
	v_mov_b64_e32 v[48:49], v[204:205]
	v_mov_b64_e32 v[50:51], v[206:207]
	v_mfma_f32_16x16x32_bf16 v[2:5], v[2:5], v[14:17], v[10:13]
	s_nop 0
	s_nop 3
	v_add_f32_e32 v37, v52, v48
	v_add_f32_e32 v47, v53, v49
	v_add_f32_e32 v48, v54, v50
	v_add_f32_e32 v49, v55, v51
	v_mul_f32_e32 v37, 0xbfb8aa3b, v37
	v_mul_f32_e32 v47, 0xbfb8aa3b, v47
	v_mul_f32_e32 v48, 0xbfb8aa3b, v48
	v_mul_f32_e32 v49, 0xbfb8aa3b, v49
	v_exp_f32_e32 v37, v37
	v_exp_f32_e32 v47, v47
	v_exp_f32_e32 v48, v48
	v_exp_f32_e32 v49, v49
	v_add_f32_e32 v37, 1.0, v37
	v_add_f32_e32 v47, 1.0, v47
	v_add_f32_e32 v48, 1.0, v48
	v_add_f32_e32 v49, 1.0, v49
	v_rcp_f32_e32 v37, v37
	v_rcp_f32_e32 v47, v47
	v_rcp_f32_e32 v48, v48
	v_rcp_f32_e32 v49, v49
	v_mul_f32_e32 v37, 0xbf1b4598, v37
	v_mul_f32_e32 v47, 0xbf1b4598, v47
	v_mul_f32_e32 v48, 0xbf1b4598, v48
	v_mul_f32_e32 v49, 0xbf1b4598, v49
	v_mul_f32_e32 v37, 0x3fb8aa3b, v37
	v_mul_f32_e32 v47, 0x3fb8aa3b, v47
	v_mul_f32_e32 v50, 0x3fb8aa3b, v48
	v_mul_f32_e32 v51, 0x3fb8aa3b, v49
	v_exp_f32_e32 v48, v37
	v_exp_f32_e32 v49, v47
	v_exp_f32_e32 v50, v50
	v_exp_f32_e32 v51, v51
	v_ashrrev_i32_e32 v37, 31, v36
	v_lshlrev_b64 v[22:23], 11, v[36:37]
	v_lshl_add_u64 v[22:23], s[4:5], 0, v[22:23]
	global_store_dwordx4 v[56:57], v[48:51], off offset:64 sc1
	s_nop 1
	v_mov_b64_e32 v[48:49], v[200:201]
	v_mov_b64_e32 v[50:51], v[202:203]
	v_lshl_add_u64 v[22:23], v[22:23], 0, v[38:39]
	s_nop 0
	v_add_f32_e32 v6, v6, v48
	v_add_f32_e32 v7, v7, v49
	v_add_f32_e32 v8, v8, v50
	v_add_f32_e32 v9, v9, v51
	v_mul_f32_e32 v6, 0xbfb8aa3b, v6
	v_mul_f32_e32 v7, 0xbfb8aa3b, v7
	v_mul_f32_e32 v8, 0xbfb8aa3b, v8
	v_mul_f32_e32 v9, 0xbfb8aa3b, v9
	v_exp_f32_e32 v6, v6
	v_exp_f32_e32 v7, v7
	v_exp_f32_e32 v8, v8
	v_exp_f32_e32 v9, v9
	v_add_f32_e32 v6, 1.0, v6
	v_add_f32_e32 v7, 1.0, v7
	v_add_f32_e32 v8, 1.0, v8
	v_add_f32_e32 v9, 1.0, v9
	v_rcp_f32_e32 v6, v6
	v_rcp_f32_e32 v7, v7
	v_rcp_f32_e32 v8, v8
	v_rcp_f32_e32 v9, v9
	v_mul_f32_e32 v6, 0xbf1b4598, v6
	v_mul_f32_e32 v7, 0xbf1b4598, v7
	v_mul_f32_e32 v8, 0xbf1b4598, v8
	v_mul_f32_e32 v9, 0xbf1b4598, v9
	v_mul_f32_e32 v6, 0x3fb8aa3b, v6
	v_mul_f32_e32 v7, 0x3fb8aa3b, v7
	v_mul_f32_e32 v8, 0x3fb8aa3b, v8
	v_mul_f32_e32 v9, 0x3fb8aa3b, v9
	v_exp_f32_e32 v6, v6
	v_exp_f32_e32 v7, v7
	v_exp_f32_e32 v8, v8
	v_exp_f32_e32 v9, v9
	global_store_dwordx4 v[22:23], v[6:9], off sc1
	s_nop 1
	v_mov_b64_e32 v[6:7], v[204:205]
	v_mov_b64_e32 v[8:9], v[206:207]
	s_nop 0
	v_add_f32_e32 v2, v2, v6
	v_add_f32_e32 v3, v3, v7
	v_add_f32_e32 v4, v4, v8
	v_add_f32_e32 v5, v5, v9
	v_mul_f32_e32 v2, 0xbfb8aa3b, v2
	v_mul_f32_e32 v3, 0xbfb8aa3b, v3
	v_mul_f32_e32 v4, 0xbfb8aa3b, v4
	v_mul_f32_e32 v5, 0xbfb8aa3b, v5
	v_exp_f32_e32 v2, v2
	v_exp_f32_e32 v3, v3
	v_exp_f32_e32 v4, v4
	v_exp_f32_e32 v5, v5
	v_add_f32_e32 v2, 1.0, v2
	v_add_f32_e32 v3, 1.0, v3
	v_add_f32_e32 v4, 1.0, v4
	v_add_f32_e32 v5, 1.0, v5
	v_rcp_f32_e32 v2, v2
	v_rcp_f32_e32 v3, v3
	v_rcp_f32_e32 v4, v4
	v_rcp_f32_e32 v5, v5
	v_mul_f32_e32 v2, 0xbf1b4598, v2
	v_mul_f32_e32 v3, 0xbf1b4598, v3
	v_mul_f32_e32 v4, 0xbf1b4598, v4
	v_mul_f32_e32 v5, 0xbf1b4598, v5
	v_mul_f32_e32 v2, 0x3fb8aa3b, v2
	v_mul_f32_e32 v3, 0x3fb8aa3b, v3
	v_mul_f32_e32 v4, 0x3fb8aa3b, v4
	v_mul_f32_e32 v5, 0x3fb8aa3b, v5
	v_exp_f32_e32 v2, v2
	v_exp_f32_e32 v3, v3
	v_exp_f32_e32 v4, v4
	v_exp_f32_e32 v5, v5
	global_store_dwordx4 v[22:23], v[2:5], off offset:64 sc1
	s_cbranch_scc1 .LBB0_2759
	s_nop 0
	v_mov_b32_e32 v2, 0
	ds_read_b64 v[2:3], v2 offset:336

.Lsgp2_issue:
	v_lshl_add_u64 v[208:209], v[208:209], 0, v[34:35]
	s_mov_b32 m0, s19
	s_nop 0
	global_load_lds_dwordx4 v[208:209], off
	v_lshl_add_u64 v[210:211], v[210:211], 0, v[34:35]
	s_mov_b32 m0, s20
	s_nop 0
	global_load_lds_dwordx4 v[210:211], off
	v_lshl_add_u64 v[212:213], v[212:213], 0, v[34:35]
	s_mov_b32 m0, s21
	s_nop 0
	global_load_lds_dwordx4 v[212:213], off
	v_lshl_add_u64 v[214:215], v[214:215], 0, v[34:35]
	s_mov_b32 m0, s22
	s_nop 0
	global_load_lds_dwordx4 v[214:215], off
	v_mfma_f32_16x16x32_bf16 v[52:55], v[6:9], v[48:51], v[52:55]
	v_add_u32_e32 v36, 48, v36
	s_add_i32 s12, s12, s56
	s_add_i32 s17, s17, s18
	v_mfma_f32_16x16x32_bf16 v[48:51], v[2:5], v[48:51], v[56:59]
	s_cmpk_lt_i32 s12, 0xc0
	v_mfma_f32_16x16x32_bf16 v[56:59], v[6:9], v[60:63], v[64:67]
	s_nop 2
	s_waitcnt vmcnt(4)
	s_nop 1
	v_mov_b64_e32 v[64:65], v[200:201]
	v_mov_b64_e32 v[66:67], v[202:203]
	v_mfma_f32_16x16x32_bf16 v[60:63], v[2:5], v[60:63], v[68:71]
	s_nop 0
	v_add_f32_e32 v37, v52, v64
	v_add_f32_e32 v47, v53, v65
	v_add_f32_e32 v52, v54, v66
	v_add_f32_e32 v53, v55, v67
	v_mul_f32_e32 v37, 0xbfb8aa3b, v37
	v_mul_f32_e32 v47, 0xbfb8aa3b, v47
	v_mul_f32_e32 v52, 0xbfb8aa3b, v52
	v_mul_f32_e32 v53, 0xbfb8aa3b, v53
	v_exp_f32_e32 v37, v37
	v_exp_f32_e32 v47, v47
	v_exp_f32_e32 v52, v52
	v_exp_f32_e32 v53, v53
	v_add_f32_e32 v37, 1.0, v37
	v_add_f32_e32 v47, 1.0, v47
	v_add_f32_e32 v52, 1.0, v52
	v_add_f32_e32 v53, 1.0, v53
	v_rcp_f32_e32 v37, v37
	v_rcp_f32_e32 v47, v47
	v_rcp_f32_e32 v52, v52
	v_rcp_f32_e32 v53, v53
	v_mul_f32_e32 v37, 0xbf1b4598, v37
	v_mul_f32_e32 v47, 0xbf1b4598, v47
	v_mul_f32_e32 v52, 0xbf1b4598, v52
	v_mul_f32_e32 v53, 0xbf1b4598, v53
	v_mul_f32_e32 v37, 0x3fb8aa3b, v37
	v_mul_f32_e32 v47, 0x3fb8aa3b, v47
	v_mul_f32_e32 v54, 0x3fb8aa3b, v52
	v_mul_f32_e32 v55, 0x3fb8aa3b, v53
	v_exp_f32_e32 v52, v37
	v_exp_f32_e32 v53, v47
	v_exp_f32_e32 v54, v54
	v_exp_f32_e32 v55, v55
	s_waitcnt lgkmcnt(1)
	v_mfma_f32_16x16x32_bf16 v[18:21], v[18:21], v[22:25], 0
	global_store_dwordx4 v[88:89], v[52:55], off sc1
	s_nop 1
	v_mov_b64_e32 v[52:53], v[204:205]
	v_mov_b64_e32 v[54:55], v[206:207]
	v_mfma_f32_16x16x32_bf16 v[10:13], v[10:13], v[22:25], 0
	s_nop 0
	v_add_f32_e32 v37, v48, v52
	v_add_f32_e32 v47, v49, v53
	v_add_f32_e32 v48, v50, v54
	v_add_f32_e32 v49, v51, v55
	v_mul_f32_e32 v37, 0xbfb8aa3b, v37
	v_mul_f32_e32 v47, 0xbfb8aa3b, v47
	v_mul_f32_e32 v48, 0xbfb8aa3b, v48
	v_mul_f32_e32 v49, 0xbfb8aa3b, v49
	v_exp_f32_e32 v37, v37
	v_exp_f32_e32 v47, v47
	v_exp_f32_e32 v48, v48
	v_exp_f32_e32 v49, v49
	v_add_f32_e32 v37, 1.0, v37
	v_add_f32_e32 v47, 1.0, v47
	v_add_f32_e32 v48, 1.0, v48
	v_add_f32_e32 v49, 1.0, v49
	v_rcp_f32_e32 v37, v37
	v_rcp_f32_e32 v47, v47
	v_rcp_f32_e32 v48, v48
	v_rcp_f32_e32 v49, v49
	v_mul_f32_e32 v37, 0xbf1b4598, v37
	v_mul_f32_e32 v47, 0xbf1b4598, v47
	v_mul_f32_e32 v48, 0xbf1b4598, v48
	v_mul_f32_e32 v49, 0xbf1b4598, v49
	v_mul_f32_e32 v37, 0x3fb8aa3b, v37
	v_mul_f32_e32 v47, 0x3fb8aa3b, v47
	v_mul_f32_e32 v50, 0x3fb8aa3b, v48
	v_mul_f32_e32 v51, 0x3fb8aa3b, v49
	v_exp_f32_e32 v48, v37
	v_exp_f32_e32 v49, v47
	v_exp_f32_e32 v50, v50
	v_exp_f32_e32 v51, v51
	v_lshlrev_b64 v[52:53], 11, v[86:87]
	v_lshl_add_u64 v[52:53], s[4:5], 0, v[52:53]
	global_store_dwordx4 v[88:89], v[48:51], off offset:64 sc1
	s_nop 1
	v_mov_b64_e32 v[48:49], v[200:201]
	v_mov_b64_e32 v[50:51], v[202:203]
	s_nop 0
	v_add_f32_e32 v37, v56, v48
	v_add_f32_e32 v47, v57, v49
	v_add_f32_e32 v48, v58, v50
	v_add_f32_e32 v49, v59, v51
	v_mul_f32_e32 v37, 0xbfb8aa3b, v37
	v_mul_f32_e32 v47, 0xbfb8aa3b, v47
	v_mul_f32_e32 v48, 0xbfb8aa3b, v48
	v_mul_f32_e32 v49, 0xbfb8aa3b, v49
	v_exp_f32_e32 v37, v37
	v_exp_f32_e32 v47, v47
	v_exp_f32_e32 v48, v48
	v_exp_f32_e32 v49, v49
	v_add_f32_e32 v37, 1.0, v37
	v_add_f32_e32 v47, 1.0, v47
	v_add_f32_e32 v48, 1.0, v48
	v_add_f32_e32 v49, 1.0, v49
	v_rcp_f32_e32 v37, v37
	v_rcp_f32_e32 v47, v47
	v_rcp_f32_e32 v48, v48
	v_rcp_f32_e32 v49, v49
	v_mul_f32_e32 v37, 0xbf1b4598, v37
	v_mul_f32_e32 v47, 0xbf1b4598, v47
	v_mul_f32_e32 v48, 0xbf1b4598, v48
	v_mul_f32_e32 v49, 0xbf1b4598, v49
	v_mul_f32_e32 v37, 0x3fb8aa3b, v37
	v_mul_f32_e32 v47, 0x3fb8aa3b, v47
	v_mul_f32_e32 v50, 0x3fb8aa3b, v48
	v_mul_f32_e32 v51, 0x3fb8aa3b, v49
	v_exp_f32_e32 v48, v37
	v_exp_f32_e32 v49, v47
	v_exp_f32_e32 v50, v50
	v_exp_f32_e32 v51, v51
	v_lshl_add_u64 v[56:57], v[52:53], 0, v[38:39]
	v_mfma_f32_16x16x32_bf16 v[52:55], v[6:9], v[72:75], v[76:79]
	global_store_dwordx4 v[84:85], v[48:51], off sc1
	s_nop 1
	v_mov_b64_e32 v[48:49], v[204:205]
	v_mov_b64_e32 v[50:51], v[206:207]
	s_waitcnt lgkmcnt(0)
	v_mfma_f32_16x16x32_bf16 v[6:9], v[6:9], v[14:17], v[18:21]
	s_nop 0
	v_add_f32_e32 v37, v60, v48
	v_add_f32_e32 v47, v61, v49
	v_add_f32_e32 v48, v62, v50
	v_add_f32_e32 v49, v63, v51
	v_mul_f32_e32 v37, 0xbfb8aa3b, v37
	v_mul_f32_e32 v47, 0xbfb8aa3b, v47
	v_mul_f32_e32 v48, 0xbfb8aa3b, v48
	v_mul_f32_e32 v49, 0xbfb8aa3b, v49
	v_exp_f32_e32 v37, v37
	v_exp_f32_e32 v47, v47
	v_exp_f32_e32 v48, v48
	v_exp_f32_e32 v49, v49
	v_add_f32_e32 v37, 1.0, v37
	v_add_f32_e32 v47, 1.0, v47
	v_add_f32_e32 v48, 1.0, v48
	v_add_f32_e32 v49, 1.0, v49
	v_rcp_f32_e32 v37, v37
	v_rcp_f32_e32 v47, v47
	v_rcp_f32_e32 v48, v48
	v_rcp_f32_e32 v49, v49
	v_mul_f32_e32 v37, 0xbf1b4598, v37
	v_mul_f32_e32 v47, 0xbf1b4598, v47
	v_mul_f32_e32 v48, 0xbf1b4598, v48
	v_mul_f32_e32 v49, 0xbf1b4598, v49
	v_mul_f32_e32 v37, 0x3fb8aa3b, v37
	v_mul_f32_e32 v47, 0x3fb8aa3b, v47
	v_mul_f32_e32 v50, 0x3fb8aa3b, v48
	v_mul_f32_e32 v51, 0x3fb8aa3b, v49
	v_exp_f32_e32 v48, v37
	v_exp_f32_e32 v49, v47
	v_exp_f32_e32 v50, v50
	v_exp_f32_e32 v51, v51
	global_store_dwordx4 v[84:85], v[48:51], off offset:64 sc1
	s_nop 1
	v_mov_b64_e32 v[48:49], v[200:201]
	v_mov_b64_e32 v[50:51], v[202:203]
	s_nop 0
	v_add_f32_e32 v37, v52, v48
	v_add_f32_e32 v47, v53, v49
	v_add_f32_e32 v48, v54, v50
	v_add_f32_e32 v49, v55, v51
	v_mul_f32_e32 v37, 0xbfb8aa3b, v37
	v_mul_f32_e32 v47, 0xbfb8aa3b, v47
	v_mul_f32_e32 v48, 0xbfb8aa3b, v48
	v_mul_f32_e32 v49, 0xbfb8aa3b, v49
	v_exp_f32_e32 v37, v37
	v_exp_f32_e32 v47, v47
	v_exp_f32_e32 v48, v48
	v_exp_f32_e32 v49, v49
	v_add_f32_e32 v37, 1.0, v37
	v_add_f32_e32 v47, 1.0, v47
	v_add_f32_e32 v48, 1.0, v48
	v_add_f32_e32 v49, 1.0, v49
	v_rcp_f32_e32 v37, v37
	v_rcp_f32_e32 v47, v47
	v_rcp_f32_e32 v48, v48
	v_rcp_f32_e32 v49, v49
	v_mul_f32_e32 v37, 0xbf1b4598, v37
	v_mul_f32_e32 v47, 0xbf1b4598, v47
	v_mul_f32_e32 v48, 0xbf1b4598, v48
	v_mul_f32_e32 v49, 0xbf1b4598, v49
	v_mul_f32_e32 v37, 0x3fb8aa3b, v37
	v_mul_f32_e32 v47, 0x3fb8aa3b, v47
	v_mul_f32_e32 v50, 0x3fb8aa3b, v48
	v_mul_f32_e32 v51, 0x3fb8aa3b, v49
	v_exp_f32_e32 v48, v37
	v_exp_f32_e32 v49, v47
	v_exp_f32_e32 v50, v50
	v_exp_f32_e32 v51, v51
	v_mfma_f32_16x16x32_bf16 v[52:55], v[2:5], v[72:75], v[80:83]
	global_store_dwordx4 v[56:57], v[48:51], off sc1
	s_nop 1
	v_mov_b64_e32 v[48:49], v[204:205]
	v_mov_b64_e32 v[50:51], v[206:207]
	v_mfma_f32_16x16x32_bf16 v[2:5], v[2:5], v[14:17], v[10:13]
	s_nop 0
	s_nop 3
	v_add_f32_e32 v37, v52, v48
	v_add_f32_e32 v47, v53, v49
	v_add_f32_e32 v48, v54, v50
	v_add_f32_e32 v49, v55, v51
	v_mul_f32_e32 v37, 0xbfb8aa3b, v37
	v_mul_f32_e32 v47, 0xbfb8aa3b, v47
	v_mul_f32_e32 v48, 0xbfb8aa3b, v48
	v_mul_f32_e32 v49, 0xbfb8aa3b, v49
	v_exp_f32_e32 v37, v37
	v_exp_f32_e32 v47, v47
	v_exp_f32_e32 v48, v48
	v_exp_f32_e32 v49, v49
	v_add_f32_e32 v37, 1.0, v37
	v_add_f32_e32 v47, 1.0, v47
	v_add_f32_e32 v48, 1.0, v48
	v_add_f32_e32 v49, 1.0, v49
	v_rcp_f32_e32 v37, v37
	v_rcp_f32_e32 v47, v47
	v_rcp_f32_e32 v48, v48
	v_rcp_f32_e32 v49, v49
	v_mul_f32_e32 v37, 0xbf1b4598, v37
	v_mul_f32_e32 v47, 0xbf1b4598, v47
	v_mul_f32_e32 v48, 0xbf1b4598, v48
	v_mul_f32_e32 v49, 0xbf1b4598, v49
	v_mul_f32_e32 v37, 0x3fb8aa3b, v37
	v_mul_f32_e32 v47, 0x3fb8aa3b, v47
	v_mul_f32_e32 v50, 0x3fb8aa3b, v48
	v_mul_f32_e32 v51, 0x3fb8aa3b, v49
	v_exp_f32_e32 v48, v37
	v_exp_f32_e32 v49, v47
	v_exp_f32_e32 v50, v50
	v_exp_f32_e32 v51, v51
	v_ashrrev_i32_e32 v37, 31, v36
	v_lshlrev_b64 v[22:23], 11, v[36:37]
	v_lshl_add_u64 v[22:23], s[4:5], 0, v[22:23]
	global_store_dwordx4 v[56:57], v[48:51], off offset:64 sc1
	s_nop 1
	v_mov_b64_e32 v[48:49], v[200:201]
	v_mov_b64_e32 v[50:51], v[202:203]
	v_lshl_add_u64 v[22:23], v[22:23], 0, v[38:39]
	s_nop 0
	v_add_f32_e32 v6, v6, v48
	v_add_f32_e32 v7, v7, v49
	v_add_f32_e32 v8, v8, v50
	v_add_f32_e32 v9, v9, v51
	v_mul_f32_e32 v6, 0xbfb8aa3b, v6
	v_mul_f32_e32 v7, 0xbfb8aa3b, v7
	v_mul_f32_e32 v8, 0xbfb8aa3b, v8
	v_mul_f32_e32 v9, 0xbfb8aa3b, v9
	v_exp_f32_e32 v6, v6
	v_exp_f32_e32 v7, v7
	v_exp_f32_e32 v8, v8
	v_exp_f32_e32 v9, v9
	v_add_f32_e32 v6, 1.0, v6
	v_add_f32_e32 v7, 1.0, v7
	v_add_f32_e32 v8, 1.0, v8
	v_add_f32_e32 v9, 1.0, v9
	v_rcp_f32_e32 v6, v6
	v_rcp_f32_e32 v7, v7
	v_rcp_f32_e32 v8, v8
	v_rcp_f32_e32 v9, v9
	v_mul_f32_e32 v6, 0xbf1b4598, v6
	v_mul_f32_e32 v7, 0xbf1b4598, v7
	v_mul_f32_e32 v8, 0xbf1b4598, v8
	v_mul_f32_e32 v9, 0xbf1b4598, v9
	v_mul_f32_e32 v6, 0x3fb8aa3b, v6
	v_mul_f32_e32 v7, 0x3fb8aa3b, v7
	v_mul_f32_e32 v8, 0x3fb8aa3b, v8
	v_mul_f32_e32 v9, 0x3fb8aa3b, v9
	v_exp_f32_e32 v6, v6
	v_exp_f32_e32 v7, v7
	v_exp_f32_e32 v8, v8
	v_exp_f32_e32 v9, v9
	global_store_dwordx4 v[22:23], v[6:9], off sc1
	s_nop 1
	v_mov_b64_e32 v[6:7], v[204:205]
	v_mov_b64_e32 v[8:9], v[206:207]
	s_nop 0
	v_add_f32_e32 v2, v2, v6
	v_add_f32_e32 v3, v3, v7
	v_add_f32_e32 v4, v4, v8
	v_add_f32_e32 v5, v5, v9
	v_mul_f32_e32 v2, 0xbfb8aa3b, v2
	v_mul_f32_e32 v3, 0xbfb8aa3b, v3
	v_mul_f32_e32 v4, 0xbfb8aa3b, v4
	v_mul_f32_e32 v5, 0xbfb8aa3b, v5
	v_exp_f32_e32 v2, v2
	v_exp_f32_e32 v3, v3
	v_exp_f32_e32 v4, v4
	v_exp_f32_e32 v5, v5
	v_add_f32_e32 v2, 1.0, v2
	v_add_f32_e32 v3, 1.0, v3
	v_add_f32_e32 v4, 1.0, v4
	v_add_f32_e32 v5, 1.0, v5
	v_rcp_f32_e32 v2, v2
	v_rcp_f32_e32 v3, v3
	v_rcp_f32_e32 v4, v4
	v_rcp_f32_e32 v5, v5
	v_mul_f32_e32 v2, 0xbf1b4598, v2
	v_mul_f32_e32 v3, 0xbf1b4598, v3
	v_mul_f32_e32 v4, 0xbf1b4598, v4
	v_mul_f32_e32 v5, 0xbf1b4598, v5
	v_mul_f32_e32 v2, 0x3fb8aa3b, v2
	v_mul_f32_e32 v3, 0x3fb8aa3b, v3
	v_mul_f32_e32 v4, 0x3fb8aa3b, v4
	v_mul_f32_e32 v5, 0x3fb8aa3b, v5
	v_exp_f32_e32 v2, v2
	v_exp_f32_e32 v3, v3
	v_exp_f32_e32 v4, v4
	v_exp_f32_e32 v5, v5
	global_store_dwordx4 v[22:23], v[2:5], off offset:64 sc1
	s_cbranch_scc1 .LBB0_2763

.Lsgp3_issue:
	v_lshl_add_u64 v[208:209], v[208:209], 0, v[26:27]
	s_mov_b32 m0, s19
	s_nop 0
	global_load_lds_dwordx4 v[208:209], off
	v_lshl_add_u64 v[210:211], v[210:211], 0, v[26:27]
	s_mov_b32 m0, s20
	s_nop 0
	global_load_lds_dwordx4 v[210:211], off
	v_lshl_add_u64 v[212:213], v[212:213], 0, v[26:27]
	s_mov_b32 m0, s21
	s_nop 0
	global_load_lds_dwordx4 v[212:213], off
	v_lshl_add_u64 v[214:215], v[214:215], 0, v[26:27]
	s_mov_b32 m0, s22
	s_nop 0
	global_load_lds_dwordx4 v[214:215], off
	s_waitcnt vmcnt(4)
	s_nop 1
	v_mov_b64_e32 v[84:85], v[200:201]
	v_mov_b64_e32 v[86:87], v[202:203]
	v_mfma_f32_16x16x32_bf16 v[48:51], v[10:13], v[44:47], v[48:51]
	s_add_i32 s17, s17, s18
	s_cmpk_lt_i32 s12, 0xc0
	v_mfma_f32_16x16x32_bf16 v[44:47], v[2:5], v[44:47], v[52:55]
	v_mfma_f32_16x16x32_bf16 v[76:79], v[38:41], v[68:71], 0
	s_nop 0
	s_nop 2
	v_add_f32_e32 v31, v48, v84
	v_add_f32_e32 v43, v49, v85
	v_add_f32_e32 v48, v50, v86
	v_add_f32_e32 v49, v51, v87
	v_mul_f32_e32 v31, 0xbfb8aa3b, v31
	v_mul_f32_e32 v43, 0xbfb8aa3b, v43
	v_mul_f32_e32 v48, 0xbfb8aa3b, v48
	v_mul_f32_e32 v49, 0xbfb8aa3b, v49
	v_exp_f32_e32 v31, v31
	v_exp_f32_e32 v43, v43
	v_exp_f32_e32 v48, v48
	v_exp_f32_e32 v49, v49
	v_add_f32_e32 v31, 1.0, v31
	v_add_f32_e32 v43, 1.0, v43
	v_add_f32_e32 v50, 1.0, v48
	v_add_f32_e32 v51, 1.0, v49
	v_rcp_f32_e32 v48, v31
	v_rcp_f32_e32 v49, v43
	v_rcp_f32_e32 v50, v50
	v_rcp_f32_e32 v51, v51
	v_mfma_f32_16x16x32_bf16 v[68:71], v[14:17], v[68:71], 0
	global_store_dwordx4 v[90:91], v[48:51], off sc1
	s_nop 1
	v_mov_b64_e32 v[48:49], v[204:205]
	v_mov_b64_e32 v[50:51], v[206:207]
	s_waitcnt lgkmcnt(1)
	v_mfma_f32_16x16x32_bf16 v[38:41], v[38:41], v[80:83], 0
	s_nop 0
	v_add_f32_e32 v31, v44, v48
	v_add_f32_e32 v43, v45, v49
	v_add_f32_e32 v44, v46, v50
	v_add_f32_e32 v45, v47, v51
	v_mul_f32_e32 v31, 0xbfb8aa3b, v31
	v_mul_f32_e32 v43, 0xbfb8aa3b, v43
	v_mul_f32_e32 v44, 0xbfb8aa3b, v44
	v_mul_f32_e32 v45, 0xbfb8aa3b, v45
	v_exp_f32_e32 v31, v31
	v_exp_f32_e32 v43, v43
	v_exp_f32_e32 v44, v44
	v_exp_f32_e32 v45, v45
	v_add_f32_e32 v31, 1.0, v31
	v_add_f32_e32 v43, 1.0, v43
	v_add_f32_e32 v46, 1.0, v44
	v_add_f32_e32 v47, 1.0, v45
	v_rcp_f32_e32 v44, v31
	v_rcp_f32_e32 v45, v43
	v_rcp_f32_e32 v46, v46
	v_rcp_f32_e32 v47, v47
	v_lshlrev_b64 v[48:49], 11, v[88:89]
	v_lshl_add_u64 v[48:49], s[4:5], 0, v[48:49]
	v_lshl_add_u64 v[52:53], v[48:49], 0, v[28:29]
	global_store_dwordx4 v[90:91], v[44:47], off offset:64 sc1
	s_nop 1
	v_mov_b64_e32 v[44:45], v[200:201]
	v_mov_b64_e32 v[46:47], v[202:203]
	v_mfma_f32_16x16x32_bf16 v[48:51], v[10:13], v[56:59], v[60:63]
	v_mfma_f32_16x16x32_bf16 v[14:17], v[14:17], v[80:83], 0
	s_nop 0
	s_nop 5
	v_add_f32_e32 v31, v48, v44
	v_add_f32_e32 v43, v49, v45
	v_add_f32_e32 v44, v50, v46
	v_add_f32_e32 v45, v51, v47
	v_mul_f32_e32 v31, 0xbfb8aa3b, v31
	v_mul_f32_e32 v43, 0xbfb8aa3b, v43
	v_mul_f32_e32 v44, 0xbfb8aa3b, v44
	v_mul_f32_e32 v45, 0xbfb8aa3b, v45
	v_exp_f32_e32 v31, v31
	v_exp_f32_e32 v43, v43
	v_exp_f32_e32 v44, v44
	v_exp_f32_e32 v45, v45
	v_add_f32_e32 v31, 1.0, v31
	v_add_f32_e32 v43, 1.0, v43
	v_add_f32_e32 v46, 1.0, v44
	v_add_f32_e32 v47, 1.0, v45
	v_rcp_f32_e32 v44, v31
	v_rcp_f32_e32 v45, v43
	v_rcp_f32_e32 v46, v46
	v_rcp_f32_e32 v47, v47
	v_mfma_f32_16x16x32_bf16 v[48:51], v[2:5], v[56:59], v[64:67]
	global_store_dwordx4 v[52:53], v[44:47], off sc1
	s_nop 1
	v_mov_b64_e32 v[44:45], v[204:205]
	v_mov_b64_e32 v[46:47], v[206:207]
	s_nop 0
	s_nop 4
	v_add_f32_e32 v31, v48, v44
	v_add_f32_e32 v43, v49, v45
	v_add_f32_e32 v44, v50, v46
	v_add_f32_e32 v45, v51, v47
	v_mul_f32_e32 v31, 0xbfb8aa3b, v31
	v_mul_f32_e32 v43, 0xbfb8aa3b, v43
	v_mul_f32_e32 v44, 0xbfb8aa3b, v44
	v_mul_f32_e32 v45, 0xbfb8aa3b, v45
	v_exp_f32_e32 v31, v31
	v_exp_f32_e32 v43, v43
	v_exp_f32_e32 v44, v44
	v_exp_f32_e32 v45, v45
	v_add_f32_e32 v31, 1.0, v31
	v_add_f32_e32 v43, 1.0, v43
	v_add_f32_e32 v46, 1.0, v44
	v_add_f32_e32 v47, 1.0, v45
	v_rcp_f32_e32 v44, v31
	v_rcp_f32_e32 v45, v43
	v_rcp_f32_e32 v46, v46
	v_rcp_f32_e32 v47, v47
	v_add_u32_e32 v48, 32, v30
	v_ashrrev_i32_e32 v49, 31, v48
	v_lshlrev_b64 v[48:49], 11, v[48:49]
	global_store_dwordx4 v[52:53], v[44:47], off offset:64 sc1
	s_nop 1
	v_mov_b64_e32 v[44:45], v[200:201]
	v_mov_b64_e32 v[46:47], v[202:203]
	v_lshl_add_u64 v[48:49], s[4:5], 0, v[48:49]
	v_lshl_add_u64 v[52:53], v[48:49], 0, v[28:29]
	v_mfma_f32_16x16x32_bf16 v[48:51], v[10:13], v[72:75], v[76:79]
	v_add_u32_e32 v30, 48, v30
	s_waitcnt lgkmcnt(0)
	v_mfma_f32_16x16x32_bf16 v[10:13], v[10:13], v[6:9], v[38:41]
	s_nop 0
	s_nop 3
	v_add_f32_e32 v31, v48, v44
	v_add_f32_e32 v43, v49, v45
	v_add_f32_e32 v44, v50, v46
	v_add_f32_e32 v45, v51, v47
	v_mul_f32_e32 v31, 0xbfb8aa3b, v31
	v_mul_f32_e32 v43, 0xbfb8aa3b, v43
	v_mul_f32_e32 v44, 0xbfb8aa3b, v44
	v_mul_f32_e32 v45, 0xbfb8aa3b, v45
	v_exp_f32_e32 v31, v31
	v_exp_f32_e32 v43, v43
	v_exp_f32_e32 v44, v44
	v_exp_f32_e32 v45, v45
	v_add_f32_e32 v31, 1.0, v31
	v_add_f32_e32 v43, 1.0, v43
	v_add_f32_e32 v46, 1.0, v44
	v_add_f32_e32 v47, 1.0, v45
	v_rcp_f32_e32 v44, v31
	v_rcp_f32_e32 v45, v43
	v_rcp_f32_e32 v46, v46
	v_rcp_f32_e32 v47, v47
	v_mfma_f32_16x16x32_bf16 v[48:51], v[2:5], v[72:75], v[68:71]
	global_store_dwordx4 v[52:53], v[44:47], off sc1
	s_nop 1
	v_mov_b64_e32 v[44:45], v[204:205]
	v_mov_b64_e32 v[46:47], v[206:207]
	v_mfma_f32_16x16x32_bf16 v[2:5], v[2:5], v[6:9], v[14:17]
	s_nop 0
	s_nop 3
	v_add_f32_e32 v31, v48, v44
	v_add_f32_e32 v43, v49, v45
	v_add_f32_e32 v44, v50, v46
	v_add_f32_e32 v45, v51, v47
	v_mul_f32_e32 v31, 0xbfb8aa3b, v31
	v_mul_f32_e32 v43, 0xbfb8aa3b, v43
	v_mul_f32_e32 v44, 0xbfb8aa3b, v44
	v_mul_f32_e32 v45, 0xbfb8aa3b, v45
	v_exp_f32_e32 v31, v31
	v_exp_f32_e32 v43, v43
	v_exp_f32_e32 v44, v44
	v_exp_f32_e32 v45, v45
	v_add_f32_e32 v31, 1.0, v31
	v_add_f32_e32 v43, 1.0, v43
	v_add_f32_e32 v46, 1.0, v44
	v_add_f32_e32 v47, 1.0, v45
	v_rcp_f32_e32 v44, v31
	v_rcp_f32_e32 v45, v43
	v_rcp_f32_e32 v46, v46
	v_rcp_f32_e32 v47, v47
	v_ashrrev_i32_e32 v31, 31, v30
	v_lshlrev_b64 v[30:31], 11, v[30:31]
	v_lshl_add_u64 v[30:31], s[4:5], 0, v[30:31]
	global_store_dwordx4 v[52:53], v[44:47], off offset:64 sc1
	s_nop 1
	v_mov_b64_e32 v[44:45], v[200:201]
	v_mov_b64_e32 v[46:47], v[202:203]
	v_lshl_add_u64 v[28:29], v[30:31], 0, v[28:29]
	s_nop 0
	v_add_f32_e32 v10, v10, v44
	v_add_f32_e32 v11, v11, v45
	v_add_f32_e32 v12, v12, v46
	v_add_f32_e32 v13, v13, v47
	v_mul_f32_e32 v10, 0xbfb8aa3b, v10
	v_mul_f32_e32 v11, 0xbfb8aa3b, v11
	v_mul_f32_e32 v12, 0xbfb8aa3b, v12
	v_mul_f32_e32 v13, 0xbfb8aa3b, v13
	v_exp_f32_e32 v10, v10
	v_exp_f32_e32 v11, v11
	v_exp_f32_e32 v12, v12
	v_exp_f32_e32 v13, v13
	v_add_f32_e32 v10, 1.0, v10
	v_add_f32_e32 v11, 1.0, v11
	v_add_f32_e32 v12, 1.0, v12
	v_add_f32_e32 v13, 1.0, v13
	v_rcp_f32_e32 v10, v10
	v_rcp_f32_e32 v11, v11
	v_rcp_f32_e32 v12, v12
	v_rcp_f32_e32 v13, v13
	global_store_dwordx4 v[28:29], v[10:13], off sc1
	s_nop 1
	v_mov_b64_e32 v[10:11], v[204:205]
	v_mov_b64_e32 v[12:13], v[206:207]
	s_nop 0
	v_add_f32_e32 v2, v2, v10
	v_add_f32_e32 v3, v3, v11
	v_add_f32_e32 v4, v4, v12
	v_add_f32_e32 v5, v5, v13
	v_mul_f32_e32 v2, 0xbfb8aa3b, v2
	v_mul_f32_e32 v3, 0xbfb8aa3b, v3
	v_mul_f32_e32 v4, 0xbfb8aa3b, v4
	v_mul_f32_e32 v5, 0xbfb8aa3b, v5
	v_exp_f32_e32 v2, v2
	v_exp_f32_e32 v3, v3
	v_exp_f32_e32 v4, v4
	v_exp_f32_e32 v5, v5
	v_add_f32_e32 v2, 1.0, v2
	v_add_f32_e32 v3, 1.0, v3
	v_add_f32_e32 v4, 1.0, v4
	v_add_f32_e32 v5, 1.0, v5
	v_rcp_f32_e32 v2, v2
	v_rcp_f32_e32 v3, v3
	v_rcp_f32_e32 v4, v4
	v_rcp_f32_e32 v5, v5
	global_store_dwordx4 v[28:29], v[2:5], off offset:64 sc1
	s_cbranch_scc1 .LBB0_2766
	s_nop 0
	v_mov_b32_e32 v2, 0
	ds_read_b64 v[2:3], v2 offset:352

.Lsgw4_go:
	s_barrier
	ds_read_b128 v[38:41], v37 offset:17408
	ds_read_b128 v[6:9], v36 offset:1024
	ds_read_b128 v[44:47], v36 offset:2048
	ds_read_b128 v[10:13], v37 offset:18432
	ds_read_b128 v[14:17], v37 offset:19456
	ds_read_b128 v[2:5], v37 offset:20480
	s_waitcnt lgkmcnt(0)
	v_mfma_f32_16x16x32_bf16 v[48:51], v[38:41], v[6:9], 0
	v_lshlrev_b64 v[64:65], 11, v[30:31]
	v_lshl_add_u64 v[80:81], s[4:5], 0, v[64:65]
	v_lshl_add_u64 v[32:33], s[2:3], 0, v[28:29]
	global_load_dwordx4 v[200:203], v[32:33], off offset:2048
	global_load_dwordx4 v[204:207], v[32:33], off offset:2112
	v_mfma_f32_16x16x32_bf16 v[52:55], v[14:17], v[6:9], 0
	ds_read_b128 v[6:9], v36 offset:3072
	ds_read_b128 v[56:59], v36 offset:4096
	ds_read_b128 v[68:71], v36 offset:5120
	ds_read_b128 v[72:75], v36 offset:6144
	v_lshl_add_u64 v[90:91], v[80:81], 0, v[28:29]
	s_waitcnt lgkmcnt(0)
	v_mfma_f32_16x16x32_bf16 v[60:63], v[38:41], v[6:9], 0
	v_add_u32_e32 v88, 16, v30
	v_ashrrev_i32_e32 v89, 31, v88
	s_add_i32 s12, s12, s56
	v_mfma_f32_16x16x32_bf16 v[64:67], v[14:17], v[6:9], 0
	ds_read_b128 v[80:83], v36 offset:7168
	ds_read_b128 v[6:9], v36 offset:8192
	s_waitcnt lgkmcnt(0)
	s_barrier
	s_waitcnt vmcnt(0)
	s_nop 1
	v_mov_b64_e32 v[84:85], v[200:201]
	v_mov_b64_e32 v[86:87], v[202:203]
	v_mfma_f32_16x16x32_bf16 v[48:51], v[10:13], v[44:47], v[48:51]
	s_add_i32 s17, s17, s18
	s_cmpk_lt_i32 s12, 0xc0
	v_mfma_f32_16x16x32_bf16 v[44:47], v[2:5], v[44:47], v[52:55]
	v_mfma_f32_16x16x32_bf16 v[76:79], v[38:41], v[68:71], 0
	s_nop 0
	s_nop 2
	v_add_f32_e32 v31, v48, v84
	v_add_f32_e32 v43, v49, v85
	v_add_f32_e32 v48, v50, v86
	v_add_f32_e32 v49, v51, v87
	v_mul_f32_e32 v31, 0xbfb8aa3b, v31
	v_mul_f32_e32 v43, 0xbfb8aa3b, v43
	v_mul_f32_e32 v48, 0xbfb8aa3b, v48
	v_mul_f32_e32 v49, 0xbfb8aa3b, v49
	v_exp_f32_e32 v31, v31
	v_exp_f32_e32 v43, v43
	v_exp_f32_e32 v48, v48
	v_exp_f32_e32 v49, v49
	v_add_f32_e32 v31, 1.0, v31
	v_add_f32_e32 v43, 1.0, v43
	v_add_f32_e32 v50, 1.0, v48
	v_add_f32_e32 v51, 1.0, v49
	v_rcp_f32_e32 v48, v31
	v_rcp_f32_e32 v49, v43
	v_rcp_f32_e32 v50, v50
	v_rcp_f32_e32 v51, v51
	v_mfma_f32_16x16x32_bf16 v[68:71], v[14:17], v[68:71], 0
	global_store_dwordx4 v[90:91], v[48:51], off sc1
	s_nop 1
	v_mov_b64_e32 v[48:49], v[204:205]
	v_mov_b64_e32 v[50:51], v[206:207]
	s_waitcnt lgkmcnt(1)
	v_mfma_f32_16x16x32_bf16 v[38:41], v[38:41], v[80:83], 0
	s_nop 0
	v_add_f32_e32 v31, v44, v48
	v_add_f32_e32 v43, v45, v49
	v_add_f32_e32 v44, v46, v50
	v_add_f32_e32 v45, v47, v51
	v_mul_f32_e32 v31, 0xbfb8aa3b, v31
	v_mul_f32_e32 v43, 0xbfb8aa3b, v43
	v_mul_f32_e32 v44, 0xbfb8aa3b, v44
	v_mul_f32_e32 v45, 0xbfb8aa3b, v45
	v_exp_f32_e32 v31, v31
	v_exp_f32_e32 v43, v43
	v_exp_f32_e32 v44, v44
	v_exp_f32_e32 v45, v45
	v_add_f32_e32 v31, 1.0, v31
	v_add_f32_e32 v43, 1.0, v43
	v_add_f32_e32 v46, 1.0, v44
	v_add_f32_e32 v47, 1.0, v45
	v_rcp_f32_e32 v44, v31
	v_rcp_f32_e32 v45, v43
	v_rcp_f32_e32 v46, v46
	v_rcp_f32_e32 v47, v47
	v_lshlrev_b64 v[48:49], 11, v[88:89]
	v_lshl_add_u64 v[48:49], s[4:5], 0, v[48:49]
	v_lshl_add_u64 v[52:53], v[48:49], 0, v[28:29]
	global_store_dwordx4 v[90:91], v[44:47], off offset:64 sc1
	s_nop 1
	v_mov_b64_e32 v[44:45], v[200:201]
	v_mov_b64_e32 v[46:47], v[202:203]
	v_mfma_f32_16x16x32_bf16 v[48:51], v[10:13], v[56:59], v[60:63]
	v_mfma_f32_16x16x32_bf16 v[14:17], v[14:17], v[80:83], 0
	s_nop 0
	s_nop 5
	v_add_f32_e32 v31, v48, v44
	v_add_f32_e32 v43, v49, v45
	v_add_f32_e32 v44, v50, v46
	v_add_f32_e32 v45, v51, v47
	v_mul_f32_e32 v31, 0xbfb8aa3b, v31
	v_mul_f32_e32 v43, 0xbfb8aa3b, v43
	v_mul_f32_e32 v44, 0xbfb8aa3b, v44
	v_mul_f32_e32 v45, 0xbfb8aa3b, v45
	v_exp_f32_e32 v31, v31
	v_exp_f32_e32 v43, v43
	v_exp_f32_e32 v44, v44
	v_exp_f32_e32 v45, v45
	v_add_f32_e32 v31, 1.0, v31
	v_add_f32_e32 v43, 1.0, v43
	v_add_f32_e32 v46, 1.0, v44
	v_add_f32_e32 v47, 1.0, v45
	v_rcp_f32_e32 v44, v31
	v_rcp_f32_e32 v45, v43
	v_rcp_f32_e32 v46, v46
	v_rcp_f32_e32 v47, v47
	v_mfma_f32_16x16x32_bf16 v[48:51], v[2:5], v[56:59], v[64:67]
	global_store_dwordx4 v[52:53], v[44:47], off sc1
	s_nop 1
	v_mov_b64_e32 v[44:45], v[204:205]
	v_mov_b64_e32 v[46:47], v[206:207]
	s_nop 0
	s_nop 4
	v_add_f32_e32 v31, v48, v44
	v_add_f32_e32 v43, v49, v45
	v_add_f32_e32 v44, v50, v46
	v_add_f32_e32 v45, v51, v47
	v_mul_f32_e32 v31, 0xbfb8aa3b, v31
	v_mul_f32_e32 v43, 0xbfb8aa3b, v43
	v_mul_f32_e32 v44, 0xbfb8aa3b, v44
	v_mul_f32_e32 v45, 0xbfb8aa3b, v45
	v_exp_f32_e32 v31, v31
	v_exp_f32_e32 v43, v43
	v_exp_f32_e32 v44, v44
	v_exp_f32_e32 v45, v45
	v_add_f32_e32 v31, 1.0, v31
	v_add_f32_e32 v43, 1.0, v43
	v_add_f32_e32 v46, 1.0, v44
	v_add_f32_e32 v47, 1.0, v45
	v_rcp_f32_e32 v44, v31
	v_rcp_f32_e32 v45, v43
	v_rcp_f32_e32 v46, v46
	v_rcp_f32_e32 v47, v47
	v_add_u32_e32 v48, 32, v30
	v_ashrrev_i32_e32 v49, 31, v48
	v_lshlrev_b64 v[48:49], 11, v[48:49]
	global_store_dwordx4 v[52:53], v[44:47], off offset:64 sc1
	s_nop 1
	v_mov_b64_e32 v[44:45], v[200:201]
	v_mov_b64_e32 v[46:47], v[202:203]
	v_lshl_add_u64 v[48:49], s[4:5], 0, v[48:49]
	v_lshl_add_u64 v[52:53], v[48:49], 0, v[28:29]
	v_mfma_f32_16x16x32_bf16 v[48:51], v[10:13], v[72:75], v[76:79]
	v_add_u32_e32 v30, 48, v30
	s_waitcnt lgkmcnt(0)
	v_mfma_f32_16x16x32_bf16 v[10:13], v[10:13], v[6:9], v[38:41]
	s_nop 0
	s_nop 3
	v_add_f32_e32 v31, v48, v44
	v_add_f32_e32 v43, v49, v45
	v_add_f32_e32 v44, v50, v46
	v_add_f32_e32 v45, v51, v47
	v_mul_f32_e32 v31, 0xbfb8aa3b, v31
	v_mul_f32_e32 v43, 0xbfb8aa3b, v43
	v_mul_f32_e32 v44, 0xbfb8aa3b, v44
	v_mul_f32_e32 v45, 0xbfb8aa3b, v45
	v_exp_f32_e32 v31, v31
	v_exp_f32_e32 v43, v43
	v_exp_f32_e32 v44, v44
	v_exp_f32_e32 v45, v45
	v_add_f32_e32 v31, 1.0, v31
	v_add_f32_e32 v43, 1.0, v43
	v_add_f32_e32 v46, 1.0, v44
	v_add_f32_e32 v47, 1.0, v45
	v_rcp_f32_e32 v44, v31
	v_rcp_f32_e32 v45, v43
	v_rcp_f32_e32 v46, v46
	v_rcp_f32_e32 v47, v47
	v_mfma_f32_16x16x32_bf16 v[48:51], v[2:5], v[72:75], v[68:71]
	global_store_dwordx4 v[52:53], v[44:47], off sc1
	s_nop 1
	v_mov_b64_e32 v[44:45], v[204:205]
	v_mov_b64_e32 v[46:47], v[206:207]
	v_mfma_f32_16x16x32_bf16 v[2:5], v[2:5], v[6:9], v[14:17]
	s_nop 0
	s_nop 3
	v_add_f32_e32 v31, v48, v44
	v_add_f32_e32 v43, v49, v45
	v_add_f32_e32 v44, v50, v46
	v_add_f32_e32 v45, v51, v47
	v_mul_f32_e32 v31, 0xbfb8aa3b, v31
	v_mul_f32_e32 v43, 0xbfb8aa3b, v43
	v_mul_f32_e32 v44, 0xbfb8aa3b, v44
	v_mul_f32_e32 v45, 0xbfb8aa3b, v45
	v_exp_f32_e32 v31, v31
	v_exp_f32_e32 v43, v43
	v_exp_f32_e32 v44, v44
	v_exp_f32_e32 v45, v45
	v_add_f32_e32 v31, 1.0, v31
	v_add_f32_e32 v43, 1.0, v43
	v_add_f32_e32 v46, 1.0, v44
	v_add_f32_e32 v47, 1.0, v45
	v_rcp_f32_e32 v44, v31
	v_rcp_f32_e32 v45, v43
	v_rcp_f32_e32 v46, v46
	v_rcp_f32_e32 v47, v47
	v_ashrrev_i32_e32 v31, 31, v30
	v_lshlrev_b64 v[30:31], 11, v[30:31]
	v_lshl_add_u64 v[30:31], s[4:5], 0, v[30:31]
	global_store_dwordx4 v[52:53], v[44:47], off offset:64 sc1
	s_nop 1
	v_mov_b64_e32 v[44:45], v[200:201]
	v_mov_b64_e32 v[46:47], v[202:203]
	v_lshl_add_u64 v[28:29], v[30:31], 0, v[28:29]
	s_nop 0
	v_add_f32_e32 v10, v10, v44
	v_add_f32_e32 v11, v11, v45
	v_add_f32_e32 v12, v12, v46
	v_add_f32_e32 v13, v13, v47
	v_mul_f32_e32 v10, 0xbfb8aa3b, v10
	v_mul_f32_e32 v11, 0xbfb8aa3b, v11
	v_mul_f32_e32 v12, 0xbfb8aa3b, v12
	v_mul_f32_e32 v13, 0xbfb8aa3b, v13
	v_exp_f32_e32 v10, v10
	v_exp_f32_e32 v11, v11
	v_exp_f32_e32 v12, v12
	v_exp_f32_e32 v13, v13
	v_add_f32_e32 v10, 1.0, v10
	v_add_f32_e32 v11, 1.0, v11
	v_add_f32_e32 v12, 1.0, v12
	v_add_f32_e32 v13, 1.0, v13
	v_rcp_f32_e32 v10, v10
	v_rcp_f32_e32 v11, v11
	v_rcp_f32_e32 v12, v12
	v_rcp_f32_e32 v13, v13
	global_store_dwordx4 v[28:29], v[10:13], off sc1
	s_nop 1
	v_mov_b64_e32 v[10:11], v[204:205]
	v_mov_b64_e32 v[12:13], v[206:207]
	s_nop 0
	v_add_f32_e32 v2, v2, v10
	v_add_f32_e32 v3, v3, v11
	v_add_f32_e32 v4, v4, v12
	v_add_f32_e32 v5, v5, v13
	v_mul_f32_e32 v2, 0xbfb8aa3b, v2
	v_mul_f32_e32 v3, 0xbfb8aa3b, v3
	v_mul_f32_e32 v4, 0xbfb8aa3b, v4
	v_mul_f32_e32 v5, 0xbfb8aa3b, v5
	v_exp_f32_e32 v2, v2
	v_exp_f32_e32 v3, v3
	v_exp_f32_e32 v4, v4
	v_exp_f32_e32 v5, v5
	v_add_f32_e32 v2, 1.0, v2
	v_add_f32_e32 v3, 1.0, v3
	v_add_f32_e32 v4, 1.0, v4
	v_add_f32_e32 v5, 1.0, v5
	v_rcp_f32_e32 v2, v2
	v_rcp_f32_e32 v3, v3
	v_rcp_f32_e32 v4, v4
	v_rcp_f32_e32 v5, v5
	global_store_dwordx4 v[28:29], v[2:5], off offset:64 sc1
	s_cbranch_scc1 .LBB0_2770

.LBB0_2775:
	s_mul_hi_i32 s2, s12, 0x2aaaaaab
	s_lshr_b32 s3, s2, 31
	s_ashr_i32 s2, s2, 3
	s_add_i32 s10, s2, s3
	s_mul_i32 s2, s10, 0xffffe800
	s_add_i32 s2, s17, s2
	s_ashr_i32 s3, s2, 31
	s_lshl_b32 s10, s10, 7
	s_ashr_i32 s11, s10, 31
	s_lshl_b64 s[28:29], s[2:3], 8
	s_add_u32 s28, s13, s28
	s_addc_u32 s29, s14, s29
	s_lshl_b64 s[34:35], s[10:11], 8
	s_add_u32 s34, s15, s34
	v_lshl_add_u64 v[2:3], s[28:29], 0, v[34:35]
	s_mov_b32 m0, s19
	s_addc_u32 s35, s16, s35
	v_lshl_add_u64 v[2:3], v[2:3], 0, v[36:37]
	v_lshl_add_u64 v[4:5], s[28:29], 0, v[38:39]
	global_load_lds_dwordx4 v[2:3], off
	v_lshl_add_u64 v[4:5], v[4:5], 0, v[36:37]
	s_mov_b32 m0, s20
	v_lshl_add_u64 v[6:7], s[34:35], 0, v[34:35]
	global_load_lds_dwordx4 v[4:5], off
	v_lshl_add_u64 v[6:7], v[6:7], 0, v[36:37]
	s_mov_b32 m0, s21
	v_lshl_add_u64 v[8:9], s[34:35], 0, v[38:39]
	global_load_lds_dwordx4 v[6:7], off
	v_lshl_add_u64 v[8:9], v[8:9], 0, v[36:37]
	s_mov_b32 m0, s22
	v_lshl_add_u64 v[2:3], v[2:3], 0, s[8:9]
	global_load_lds_dwordx4 v[8:9], off
	s_mov_b32 m0, s23
	s_nop 0
	global_load_lds_dwordx4 v[2:3], off
	v_lshl_add_u64 v[2:3], v[4:5], 0, s[8:9]
	s_mov_b32 m0, s24
	s_nop 0
	global_load_lds_dwordx4 v[2:3], off
	v_lshl_add_u64 v[2:3], v[6:7], 0, s[8:9]
	s_mov_b32 m0, s25
	s_nop 0
	global_load_lds_dwordx4 v[2:3], off
	v_lshl_add_u64 v[2:3], v[8:9], 0, s[8:9]
	s_mov_b32 m0, s26
	s_nop 0
	global_load_lds_dwordx4 v[2:3], off
	s_waitcnt vmcnt(4)
	s_barrier
	ds_read_b128 v[2:5], v49 offset:17408
	ds_read_b128 v[6:9], v48 offset:1024
	ds_read_b128 v[10:13], v48 offset:2048
	ds_read_b128 v[14:17], v49 offset:18432
	ds_read_b128 v[22:25], v49 offset:19456
	ds_read_b128 v[26:29], v49 offset:20480
	ds_read_b128 v[30:33], v48 offset:3072
	ds_read_b128 v[40:43], v48 offset:4096
	ds_read_b128 v[54:57], v48 offset:5120
	ds_read_b128 v[58:61], v48 offset:6144
	ds_read_b128 v[66:69], v48 offset:7168
	ds_read_b128 v[70:73], v48 offset:8192
	s_waitcnt lgkmcnt(0)
	v_mfma_f32_16x16x32_bf16 v[18:21], v[2:5], v[6:9], 0
	s_waitcnt lgkmcnt(0)
	s_barrier
	v_mfma_f32_16x16x32_bf16 v[6:9], v[22:25], v[6:9], 0
	s_waitcnt vmcnt(0)
	s_barrier
	v_mfma_f32_16x16x32_bf16 v[50:53], v[2:5], v[30:33], 0
	v_mfma_f32_16x16x32_bf16 v[30:33], v[22:25], v[30:33], 0
	v_mfma_f32_16x16x32_bf16 v[62:65], v[2:5], v[54:57], 0
	v_mfma_f32_16x16x32_bf16 v[2:5], v[2:5], v[66:69], 0
	v_mfma_f32_16x16x32_bf16 v[18:21], v[14:17], v[10:13], v[18:21]
	v_mfma_f32_16x16x32_bf16 v[6:9], v[26:29], v[10:13], v[6:9]
	v_mfma_f32_16x16x32_bf16 v[10:13], v[14:17], v[40:43], v[50:53]
	v_mfma_f32_16x16x32_bf16 v[30:33], v[26:29], v[40:43], v[30:33]
	v_mfma_f32_16x16x32_bf16 v[40:43], v[14:17], v[58:61], v[62:65]
	v_mfma_f32_16x16x32_bf16 v[2:5], v[14:17], v[70:73], v[2:5]
	ds_read_b128 v[14:17], v49 offset:50176
	v_mfma_f32_16x16x32_bf16 v[54:57], v[22:25], v[54:57], 0
	v_mfma_f32_16x16x32_bf16 v[22:25], v[22:25], v[66:69], 0
	v_mfma_f32_16x16x32_bf16 v[50:53], v[26:29], v[58:61], v[54:57]
	v_mfma_f32_16x16x32_bf16 v[22:25], v[26:29], v[70:73], v[22:25]
	ds_read_b128 v[26:29], v48 offset:33792
	s_nop 3
	ds_read_b128 v[54:57], v48 offset:34816
	ds_read_b128 v[58:61], v49 offset:51200
	ds_read_b128 v[62:65], v49 offset:52224
	ds_read_b128 v[66:69], v49 offset:53248
	s_waitcnt lgkmcnt(0)
	v_mfma_f32_16x16x32_bf16 v[18:21], v[14:17], v[26:29], v[18:21]
	v_mfma_f32_16x16x32_bf16 v[6:9], v[62:65], v[26:29], v[6:9]
	ds_read_b128 v[26:29], v48 offset:35840
	ds_read_b128 v[70:73], v48 offset:36864
	s_waitcnt lgkmcnt(0)
	v_mfma_f32_16x16x32_bf16 v[10:13], v[14:17], v[26:29], v[10:13]
	v_mfma_f32_16x16x32_bf16 v[74:77], v[62:65], v[26:29], v[30:33]
	ds_read_b128 v[26:29], v48 offset:37888
	ds_read_b128 v[78:81], v48 offset:38912
	s_waitcnt lgkmcnt(0)
	v_mfma_f32_16x16x32_bf16 v[40:43], v[14:17], v[26:29], v[40:43]
	v_mfma_f32_16x16x32_bf16 v[50:53], v[62:65], v[26:29], v[50:53]
	ds_read_b128 v[26:29], v48 offset:39936
	ds_read_b128 v[82:85], v48 offset:40960
	s_waitcnt lgkmcnt(0)
	s_barrier
	s_waitcnt lgkmcnt(0)
	v_mfma_f32_16x16x32_bf16 v[2:5], v[14:17], v[26:29], v[2:5]
	v_mfma_f32_16x16x32_bf16 v[62:65], v[62:65], v[26:29], v[22:25]
	v_mfma_f32_16x16x32_bf16 v[14:17], v[58:61], v[78:81], v[40:43]
	s_nop 2
	v_add_u32_e32 v42, s2, v47
	v_ashrrev_i32_e32 v43, 31, v42
	v_mfma_f32_16x16x32_bf16 v[26:29], v[66:69], v[54:57], v[6:9]
	v_or_b32_e32 v40, s10, v46
	v_cmp_gt_i32_e32 vcc, s27, v40
	v_ashrrev_i32_e32 v41, 31, v40
	v_mfma_f32_16x16x32_bf16 v[6:9], v[58:61], v[82:85], v[2:5]
	s_nop 2
	v_lshlrev_b64 v[2:3], 11, v[42:43]
	v_mfma_f32_16x16x32_bf16 v[30:33], v[58:61], v[54:57], v[18:21]
	v_lshl_add_u64 v[44:45], s[6:7], 0, v[2:3]
	v_mfma_f32_16x16x32_bf16 v[22:25], v[58:61], v[70:73], v[10:13]
	v_mfma_f32_16x16x32_bf16 v[18:21], v[66:69], v[70:73], v[74:77]
	v_mfma_f32_16x16x32_bf16 v[10:13], v[66:69], v[78:81], v[50:53]
	v_mfma_f32_16x16x32_bf16 v[2:5], v[66:69], v[82:85], v[62:65]
	s_and_saveexec_b64 s[2:3], vcc
	s_cbranch_execz .LBB0_2777
	v_lshl_add_u64 v[50:51], v[40:41], 2, v[44:45]
	global_store_dwordx4 v[50:51], v[30:33], off sc1
.LBB0_2777:
	s_or_b64 exec, exec, s[2:3]
	s_nop 0
	v_or_b32_e32 v30, 16, v40
	v_cmp_gt_i32_e64 s[2:3], s27, v30
	s_and_saveexec_b64 s[10:11], s[2:3]
	s_cbranch_execz .LBB0_2779
	v_lshl_add_u64 v[30:31], v[40:41], 2, v[44:45]
	global_store_dwordx4 v[30:31], v[26:29], off offset:64 sc1
.LBB0_2779:
	s_or_b64 exec, exec, s[10:11]
	s_nop 0
	v_add_u32_e32 v26, 16, v42
	v_ashrrev_i32_e32 v27, 31, v26
	v_lshlrev_b64 v[26:27], 11, v[26:27]
	v_lshl_add_u64 v[26:27], s[6:7], 0, v[26:27]
	s_and_saveexec_b64 s[10:11], vcc
	s_cbranch_execz .LBB0_2781
	v_lshl_add_u64 v[28:29], v[40:41], 2, v[26:27]
	global_store_dwordx4 v[28:29], v[22:25], off sc1
.LBB0_2781:
	s_or_b64 exec, exec, s[10:11]
	s_and_saveexec_b64 s[10:11], s[2:3]
	s_cbranch_execz .LBB0_2783
	v_lshl_add_u64 v[22:23], v[40:41], 2, v[26:27]
	global_store_dwordx4 v[22:23], v[18:21], off offset:64 sc1
.LBB0_2783:
	s_or_b64 exec, exec, s[10:11]
	s_nop 0
	v_add_u32_e32 v18, 32, v42
	v_ashrrev_i32_e32 v19, 31, v18
	v_lshlrev_b64 v[18:19], 11, v[18:19]
	v_lshl_add_u64 v[18:19], s[6:7], 0, v[18:19]
	s_and_saveexec_b64 s[10:11], vcc
	s_cbranch_execz .LBB0_2785
	v_lshl_add_u64 v[20:21], v[40:41], 2, v[18:19]
	global_store_dwordx4 v[20:21], v[14:17], off sc1
.LBB0_2785:
	s_or_b64 exec, exec, s[10:11]
	s_and_saveexec_b64 s[10:11], s[2:3]
	s_cbranch_execz .LBB0_2787
	v_lshl_add_u64 v[14:15], v[40:41], 2, v[18:19]
	global_store_dwordx4 v[14:15], v[10:13], off offset:64 sc1
.LBB0_2787:
	s_or_b64 exec, exec, s[10:11]
	s_nop 0
	v_add_u32_e32 v10, 48, v42
	v_ashrrev_i32_e32 v11, 31, v10
	v_lshlrev_b64 v[10:11], 11, v[10:11]
	v_lshl_add_u64 v[10:11], s[6:7], 0, v[10:11]
	s_and_saveexec_b64 s[10:11], vcc
	s_cbranch_execz .LBB0_2789
	v_lshl_add_u64 v[12:13], v[40:41], 2, v[10:11]
	global_store_dwordx4 v[12:13], v[6:9], off sc1
.LBB0_2789:
	s_or_b64 exec, exec, s[10:11]
	s_and_saveexec_b64 s[10:11], s[2:3]
	s_cbranch_execz .LBB0_2774
	v_lshl_add_u64 v[6:7], v[40:41], 2, v[10:11]
	global_store_dwordx4 v[6:7], v[2:5], off offset:64 sc1
	s_branch .LBB0_2774
